# ssd_stage (passA and passB): A_log load issued together with the two dt loads instead of after the softplus (one exposed memory latency fewer per unit)
# baseline (speedup 1.0000x reference)
; template <bool PASSA> __device__ __forceinline__ void ssd_stage(const Ptrs& P, int l, int b, int ch, int gg, unsigned char* lds, int tid) {
;     ...
;     { const int hh = tid >> 7, li = tid & 127; const int h = gg * 4 + hh; float dt = 0.f, dA = 0.f;
;       if (li < nvalid) { const int row = (ch == 0) ? (MMAIN + b * NMETA + li) : (b * SEQ + 128 * (ch - 1) + li);
;           const float* dtraw = (const float*)((const unsigned char*)P.out + DO_DTRAW);
;           const float raw = dtraw[(size_t)row * 16 + h] + P.ssd_dt_bias[l * 16 + h];
;           dt = raw > 20.f ? raw : log1pf(__expf(raw)); dA = -dt * __expf(P.ssd_a_log[l * 16 + h]); }
;       DTS[hh * 128 + li] = dt; ACS[hh * 128 + li] = dA; }
.LBB0_494:
	v_ashrrev_i32_e32 v11, 7, v98
	v_add_u32_e32 v12, s10, v11
	v_mov_b32_e32 v11, v16
	v_lshlrev_b64 v[10:11], 6, v[10:11]
	v_ashrrev_i32_e32 v13, 31, v12
	v_lshl_add_u64 v[10:11], v[90:91], 0, v[10:11]
	v_lshl_add_u64 v[10:11], v[12:13], 2, v[10:11]
	global_load_dword v17, v[10:11], off
	v_add_u32_e32 v10, s14, v12
	v_ashrrev_i32_e32 v11, 31, v10
	v_lshl_add_u64 v[12:13], v[10:11], 2, v[6:7]
	global_load_dword v12, v[12:13], off
	v_lshl_add_u64 v[130:131], v[10:11], 2, v[84:85]
	global_load_dword v128, v[130:131], off
	s_mov_b32 s3, 0x41a00000
	s_waitcnt vmcnt(0)
	v_add_f32_e32 v12, v17, v12
	v_cmp_nlt_f32_e32 vcc, s3, v12
	s_and_saveexec_b64 s[4:5], vcc
	s_cbranch_execz .LBB0_496
	v_mul_f32_e32 v12, 0x3fb8aa3b, v12
	v_exp_f32_e32 v17, v12
	s_mov_b32 s3, 0x3f2aaaab
	v_add_f32_e32 v18, 1.0, v17
	v_frexp_mant_f32_e32 v20, v18
	v_cvt_f64_f32_e32 v[12:13], v18
	v_frexp_exp_i32_f64_e32 v12, v[12:13]
	v_cmp_gt_f32_e32 vcc, s3, v20
	v_add_f32_e32 v19, -1.0, v18
	v_sub_f32_e32 v21, v19, v18
	v_subbrev_co_u32_e32 v24, vcc, 0, v12, vcc
	v_sub_u32_e32 v12, 0, v24
	v_sub_f32_e32 v19, v17, v19
	v_add_f32_e32 v21, 1.0, v21
	v_ldexp_f32 v13, v18, v12
	v_add_f32_e32 v19, v19, v21
	v_add_f32_e32 v18, -1.0, v13
	v_add_f32_e32 v20, 1.0, v13
	v_ldexp_f32 v12, v19, v12
	v_add_f32_e32 v19, 1.0, v18
	v_add_f32_e32 v21, -1.0, v20
	v_sub_f32_e32 v19, v13, v19
	v_sub_f32_e32 v13, v13, v21
	v_add_f32_e32 v19, v12, v19
	v_add_f32_e32 v12, v12, v13
	v_add_f32_e32 v25, v20, v12
	v_rcp_f32_e32 v27, v25
	v_sub_f32_e32 v13, v25, v20
	v_sub_f32_e32 v26, v12, v13
	v_add_f32_e32 v13, v18, v19
	v_mul_f32_e32 v29, v13, v27
	v_sub_f32_e32 v12, v13, v18
	v_mul_f32_e32 v18, v25, v29
	v_fma_f32 v20, v29, v25, -v18
	v_fmac_f32_e32 v20, v29, v26
	v_sub_f32_e32 v28, v19, v12
	v_add_f32_e32 v12, v18, v20
	v_sub_f32_e32 v19, v13, v12
	v_pk_add_f32 v[22:23], v[12:13], v[18:19] neg_lo:[0,1] neg_hi:[0,1]
	v_mov_b32_e32 v21, v12
	v_pk_add_f32 v[12:13], v[22:23], v[20:21] neg_lo:[0,1] neg_hi:[0,1]
	s_mov_b32 s3, 0x3f317218
	v_add_f32_e32 v13, v28, v13
	v_add_f32_e32 v12, v12, v13
	v_add_f32_e32 v13, v19, v12
	v_mul_f32_e32 v28, v27, v13
	v_mul_f32_e32 v18, v25, v28
	v_fma_f32 v20, v28, v25, -v18
	v_fmac_f32_e32 v20, v28, v26
	v_sub_f32_e32 v19, v19, v13
	v_add_f32_e32 v25, v12, v19
	v_add_f32_e32 v12, v18, v20
	v_sub_f32_e32 v19, v13, v12
	v_pk_add_f32 v[22:23], v[12:13], v[18:19] neg_lo:[0,1] neg_hi:[0,1]
	v_mov_b32_e32 v21, v12
	v_pk_add_f32 v[12:13], v[22:23], v[20:21] neg_lo:[0,1] neg_hi:[0,1]
	s_nop 0
	v_add_f32_e32 v13, v25, v13
	v_add_f32_e32 v12, v12, v13
	v_add_f32_e32 v13, v29, v28
	v_add_f32_e32 v12, v19, v12
	v_sub_f32_e32 v18, v13, v29
	v_mul_f32_e32 v12, v27, v12
	v_sub_f32_e32 v18, v28, v18
	v_add_f32_e32 v18, v18, v12
	v_add_f32_e32 v20, v13, v18
	v_mul_f32_e32 v21, v20, v20
	v_fmamk_f32 v12, v21, 0x3e9b6dac, v238
	v_fmaak_f32 v195, v21, v12, 0x3f2aaada
	v_cvt_f32_i32_e32 v12, v24
	v_sub_f32_e32 v13, v20, v13
	v_sub_f32_e32 v13, v18, v13
	v_ldexp_f32 v22, v13, 1
	v_mul_f32_e32 v13, v20, v21
	v_ldexp_f32 v19, v20, 1
	v_pk_mul_f32 v[20:21], v[12:13], v[194:195]
	s_nop 0
	v_fma_f32 v18, v12, s3, -v20
	v_fmac_f32_e32 v18, 0xb102e308, v12
	v_pk_add_f32 v[12:13], v[20:21], v[18:19]
	s_mov_b32 s3, 0x7f800000
	v_sub_f32_e32 v19, v13, v19
	v_sub_f32_e32 v19, v21, v19
	v_add_f32_e32 v23, v22, v19
	v_mov_b32_e32 v22, v20
	v_pk_add_f32 v[20:21], v[12:13], v[20:21] neg_lo:[0,1] neg_hi:[0,1]
	v_pk_add_f32 v[24:25], v[12:13], v[22:23]
	v_mov_b32_e32 v19, v12
	v_mov_b32_e32 v21, v25
	v_pk_add_f32 v[26:27], v[18:19], v[20:21] neg_lo:[0,1] neg_hi:[0,1]
	v_pk_add_f32 v[18:19], v[18:19], v[20:21]
	v_mov_b32_e32 v22, v23
	v_pk_add_f32 v[20:21], v[18:19], v[12:13] op_sel:[1,0] op_sel_hi:[0,1] neg_lo:[0,1] neg_hi:[0,1]
	v_pk_add_f32 v[28:29], v[24:25], v[20:21] op_sel_hi:[1,0] neg_lo:[0,1] neg_hi:[0,1]
	v_mov_b32_e32 v24, v25
	v_mov_b32_e32 v25, v19
	v_pk_mov_b32 v[20:21], v[12:13], v[20:21] op_sel:[1,0]
	v_mov_b32_e32 v23, v12
	v_pk_add_f32 v[20:21], v[24:25], v[20:21] neg_lo:[0,1] neg_hi:[0,1]
	v_mov_b32_e32 v28, v26
	v_pk_add_f32 v[12:13], v[22:23], v[20:21] neg_lo:[0,1] neg_hi:[0,1]
	v_mov_b32_e32 v27, v19
	v_pk_add_f32 v[20:21], v[28:29], v[12:13]
	v_cmp_neq_f32_e32 vcc, s3, v17
	v_pk_add_f32 v[22:23], v[20:21], v[20:21] op_sel:[0,1] op_sel_hi:[1,0]
	s_mov_b32 s3, 0x33800000
	v_pk_add_f32 v[18:19], v[18:19], v[22:23] op_sel:[1,0] op_sel_hi:[0,1]
	v_mov_b32_e32 v21, v18
	v_pk_add_f32 v[24:25], v[20:21], v[26:27] neg_lo:[0,1] neg_hi:[0,1]
	v_mov_b32_e32 v13, v22
	v_sub_f32_e32 v19, v20, v24
	v_pk_add_f32 v[12:13], v[12:13], v[24:25] neg_lo:[0,1] neg_hi:[0,1]
	v_sub_f32_e32 v19, v26, v19
	v_add_f32_e32 v12, v12, v19
	v_add_f32_e32 v12, v12, v13
	v_add_f32_e32 v12, v18, v12
	v_cndmask_b32_e32 v12, v237, v12, vcc
	v_cmp_ngt_f32_e32 vcc, -1.0, v17
	s_nop 1
	v_cndmask_b32_e32 v12, v243, v12, vcc
	v_cmp_neq_f32_e32 vcc, -1.0, v17
	s_nop 1
	v_cndmask_b32_e32 v12, v240, v12, vcc
	v_cmp_lt_f32_e64 vcc, |v17|, s3
	s_nop 1
	v_cndmask_b32_e32 v12, v12, v17, vcc
.LBB0_496:
	s_or_b64 exec, exec, s[4:5]
	v_mov_b32_e32 v10, v128
	s_waitcnt vmcnt(0)
	v_mul_f32_e32 v10, 0x3fb8aa3b, v10
	v_exp_f32_e32 v10, v10
	s_nop 0
	v_mul_f32_e64 v13, v10, -v12

; template <bool PASSA> __device__ __forceinline__ void ssd_stage(const Ptrs& P, int l, int b, int ch, int gg, unsigned char* lds, int tid) {
;     ...
;     { const int hh = tid >> 7, li = tid & 127; const int h = gg * 4 + hh; float dt = 0.f, dA = 0.f;
;       if (li < nvalid) { const int row = (ch == 0) ? (MMAIN + b * NMETA + li) : (b * SEQ + 128 * (ch - 1) + li);
;           const float* dtraw = (const float*)((const unsigned char*)P.out + DO_DTRAW);
;           const float raw = dtraw[(size_t)row * 16 + h] + P.ssd_dt_bias[l * 16 + h];
;           dt = raw > 20.f ? raw : log1pf(__expf(raw)); dA = -dt * __expf(P.ssd_a_log[l * 16 + h]); }
;       DTS[hh * 128 + li] = dt; ACS[hh * 128 + li] = dA; }
.LBB0_938:
	v_and_b32_e32 v9, 0x7f, v211
	s_add_i32 s18, s18, 0x8000
	v_cmp_gt_u32_e32 vcc, s14, v9
	v_mov_b32_e32 v8, 0
	v_mov_b32_e32 v10, 0
	s_and_saveexec_b64 s[4:5], vcc
	s_cbranch_execz .LBB0_942
	s_add_i32 s6, s10, s15
	s_addk_i32 s6, 0xff80
	v_add_u32_e32 v10, s18, v9
	v_or_b32_e32 v9, s6, v9
	v_cndmask_b32_e64 v10, v10, v9, s[40:41]
	v_ashrrev_i32_e32 v8, 7, v211
	v_ashrrev_i32_e32 v11, 31, v10
	v_lshl_add_u32 v8, s3, 2, v8
	v_lshlrev_b64 v[10:11], 6, v[10:11]
	v_ashrrev_i32_e32 v9, 31, v8
	v_lshl_add_u64 v[10:11], v[170:171], 0, v[10:11]
	v_lshl_add_u64 v[10:11], v[8:9], 2, v[10:11]
	v_add_u32_e32 v8, s12, v8
	v_ashrrev_i32_e32 v9, 31, v8
	global_load_dword v12, v[10:11], off
	v_lshl_add_u64 v[10:11], v[8:9], 2, v[4:5]
	global_load_dword v10, v[10:11], off
	v_lshl_add_u64 v[130:131], v[8:9], 2, v[6:7]
	global_load_dword v128, v[130:131], off
	s_mov_b32 s6, 0x41a00000
	s_waitcnt vmcnt(0)
	v_add_f32_e32 v10, v12, v10
	v_cmp_nlt_f32_e32 vcc, s6, v10
	s_and_saveexec_b64 s[6:7], vcc
	s_cbranch_execz .LBB0_941
	v_mul_f32_e32 v10, 0x3fb8aa3b, v10
	v_exp_f32_e32 v17, v10
	s_mov_b32 s8, 0x3f2aaaab
	v_add_f32_e32 v12, 1.0, v17
	v_frexp_mant_f32_e32 v14, v12
	v_cvt_f64_f32_e32 v[10:11], v12
	v_frexp_exp_i32_f64_e32 v10, v[10:11]
	v_cmp_gt_f32_e32 vcc, s8, v14
	v_add_f32_e32 v13, -1.0, v12
	v_sub_f32_e32 v15, v13, v12
	v_subbrev_co_u32_e32 v20, vcc, 0, v10, vcc
	v_sub_u32_e32 v10, 0, v20
	v_sub_f32_e32 v13, v17, v13
	v_add_f32_e32 v15, 1.0, v15
	v_ldexp_f32 v11, v12, v10
	v_add_f32_e32 v13, v13, v15
	v_add_f32_e32 v12, -1.0, v11
	v_add_f32_e32 v14, 1.0, v11
	v_ldexp_f32 v10, v13, v10
	v_add_f32_e32 v13, 1.0, v12
	v_add_f32_e32 v15, -1.0, v14
	v_sub_f32_e32 v13, v11, v13
	v_sub_f32_e32 v11, v11, v15
	v_add_f32_e32 v13, v10, v13
	v_add_f32_e32 v10, v10, v11
	v_add_f32_e32 v21, v14, v10
	v_rcp_f32_e32 v23, v21
	v_sub_f32_e32 v11, v21, v14
	v_sub_f32_e32 v22, v10, v11
	v_add_f32_e32 v11, v12, v13
	v_mul_f32_e32 v25, v11, v23
	v_sub_f32_e32 v10, v11, v12
	v_mul_f32_e32 v12, v21, v25
	v_fma_f32 v14, v25, v21, -v12
	v_fmac_f32_e32 v14, v25, v22
	v_sub_f32_e32 v24, v13, v10
	v_add_f32_e32 v10, v12, v14
	v_sub_f32_e32 v13, v11, v10
	v_pk_add_f32 v[18:19], v[10:11], v[12:13] neg_lo:[0,1] neg_hi:[0,1]
	v_mov_b32_e32 v15, v10
	v_pk_add_f32 v[10:11], v[18:19], v[14:15] neg_lo:[0,1] neg_hi:[0,1]
	s_mov_b32 s8, 0x3f317218
	v_add_f32_e32 v11, v24, v11
	v_add_f32_e32 v10, v10, v11
	v_add_f32_e32 v11, v13, v10
	v_mul_f32_e32 v24, v23, v11
	v_mul_f32_e32 v12, v21, v24
	v_fma_f32 v14, v24, v21, -v12
	v_fmac_f32_e32 v14, v24, v22
	v_sub_f32_e32 v13, v13, v11
	v_add_f32_e32 v21, v10, v13
	v_add_f32_e32 v10, v12, v14
	v_sub_f32_e32 v13, v11, v10
	v_pk_add_f32 v[18:19], v[10:11], v[12:13] neg_lo:[0,1] neg_hi:[0,1]
	v_mov_b32_e32 v15, v10
	v_pk_add_f32 v[10:11], v[18:19], v[14:15] neg_lo:[0,1] neg_hi:[0,1]
	s_nop 0
	v_add_f32_e32 v11, v21, v11
	v_add_f32_e32 v10, v10, v11
	v_add_f32_e32 v11, v25, v24
	v_add_f32_e32 v10, v13, v10
	v_sub_f32_e32 v12, v11, v25
	v_mul_f32_e32 v10, v23, v10
	v_sub_f32_e32 v12, v24, v12
	v_add_f32_e32 v12, v12, v10
	v_add_f32_e32 v14, v11, v12
	v_mul_f32_e32 v15, v14, v14
	v_fmamk_f32 v10, v15, 0x3e9b6dac, v238
	v_fmaak_f32 v195, v15, v10, 0x3f2aaada
	v_cvt_f32_i32_e32 v10, v20
	v_sub_f32_e32 v11, v14, v11
	v_sub_f32_e32 v11, v12, v11
	v_ldexp_f32 v18, v11, 1
	v_mul_f32_e32 v11, v14, v15
	v_ldexp_f32 v13, v14, 1
	v_pk_mul_f32 v[14:15], v[10:11], v[194:195]
	s_nop 0
	v_fma_f32 v12, v10, s8, -v14
	v_fmac_f32_e32 v12, 0xb102e308, v10
	v_pk_add_f32 v[10:11], v[14:15], v[12:13]
	s_mov_b32 s8, 0x7f800000
	v_sub_f32_e32 v13, v11, v13
	v_sub_f32_e32 v13, v15, v13
	v_add_f32_e32 v19, v18, v13
	v_mov_b32_e32 v18, v14
	v_pk_add_f32 v[14:15], v[10:11], v[14:15] neg_lo:[0,1] neg_hi:[0,1]
	v_pk_add_f32 v[20:21], v[10:11], v[18:19]
	v_mov_b32_e32 v13, v10
	v_mov_b32_e32 v15, v21
	v_pk_add_f32 v[22:23], v[12:13], v[14:15] neg_lo:[0,1] neg_hi:[0,1]
	v_pk_add_f32 v[12:13], v[12:13], v[14:15]
	v_mov_b32_e32 v18, v19
	v_pk_add_f32 v[14:15], v[12:13], v[10:11] op_sel:[1,0] op_sel_hi:[0,1] neg_lo:[0,1] neg_hi:[0,1]
	v_pk_add_f32 v[24:25], v[20:21], v[14:15] op_sel_hi:[1,0] neg_lo:[0,1] neg_hi:[0,1]
	v_mov_b32_e32 v20, v21
	v_mov_b32_e32 v21, v13
	v_pk_mov_b32 v[14:15], v[10:11], v[14:15] op_sel:[1,0]
	v_mov_b32_e32 v19, v10
	v_pk_add_f32 v[14:15], v[20:21], v[14:15] neg_lo:[0,1] neg_hi:[0,1]
	v_mov_b32_e32 v24, v22
	v_pk_add_f32 v[10:11], v[18:19], v[14:15] neg_lo:[0,1] neg_hi:[0,1]
	v_mov_b32_e32 v23, v13
	v_pk_add_f32 v[14:15], v[24:25], v[10:11]
	v_cmp_neq_f32_e32 vcc, s8, v17
	v_pk_add_f32 v[18:19], v[14:15], v[14:15] op_sel:[0,1] op_sel_hi:[1,0]
	s_mov_b32 s8, 0x33800000
	v_pk_add_f32 v[12:13], v[12:13], v[18:19] op_sel:[1,0] op_sel_hi:[0,1]
	v_mov_b32_e32 v15, v12
	v_pk_add_f32 v[20:21], v[14:15], v[22:23] neg_lo:[0,1] neg_hi:[0,1]
	v_mov_b32_e32 v11, v18
	v_sub_f32_e32 v13, v14, v20
	v_pk_add_f32 v[10:11], v[10:11], v[20:21] neg_lo:[0,1] neg_hi:[0,1]
	v_sub_f32_e32 v13, v22, v13
	v_add_f32_e32 v10, v10, v13
	v_add_f32_e32 v10, v10, v11
	v_add_f32_e32 v10, v12, v10
	v_cndmask_b32_e32 v10, v237, v10, vcc
	v_cmp_ngt_f32_e32 vcc, -1.0, v17
	s_nop 1
	v_cndmask_b32_e32 v10, v243, v10, vcc
	v_cmp_neq_f32_e32 vcc, -1.0, v17
	s_nop 1
	v_cndmask_b32_e32 v10, v240, v10, vcc
	v_cmp_lt_f32_e64 vcc, |v17|, s8
	s_nop 1
	v_cndmask_b32_e32 v10, v10, v17, vcc
.LBB0_941:
	s_or_b64 exec, exec, s[6:7]
	v_mov_b32_e32 v8, v128
	s_waitcnt vmcnt(0)
	v_mul_f32_e32 v8, 0x3fb8aa3b, v8
	v_exp_f32_e32 v8, v8
	s_nop 0
	v_mul_f32_e64 v8, v8, -v10
